# lgk2
# baseline (speedup 1.0000x reference)
.LBB0_538:
	s_or_b64 exec, exec, s[26:27]
	s_cmp_gt_i32 s10, 7
	s_cbranch_scc1 .LBB0_541
	s_add_i32 s9, s19, s36
	s_cmpk_gt_i32 s9, 0x3fff
	s_cselect_b32 s23, s6, s9
	s_cselect_b32 s9, s33, 0
	s_add_i32 s22, s9, s7
	s_and_b64 s[16:17], s[24:25], exec
	s_cselect_b32 s24, s19, s8
	s_cselect_b32 s16, s7, s10
	s_ashr_i32 s25, s24, 31
	s_lshl_b64 s[26:27], s[24:25], 10
	s_add_u32 s9, s28, s26
	s_addc_u32 s11, s29, s27
	s_lshl_b32 s17, s16, 7
	s_ashr_i32 s27, s17, 31
	s_add_u32 s26, s9, s17
	v_lshl_or_b32 v0, s16, 21, v154
	s_addc_u32 s27, s11, s27
	s_ashr_i32 s17, s16, 31
	s_lshl_b64 s[24:25], s[24:25], 5
	s_waitcnt vmcnt(2)
	ds_swizzle_b32 v108, v240 offset:24
	ds_swizzle_b32 v109, v241 offset:24
	ds_swizzle_b32 v110, v240 offset:56
	ds_swizzle_b32 v111, v241 offset:56
	ds_swizzle_b32 v92, v240 offset:88
	ds_swizzle_b32 v93, v241 offset:88
	ds_swizzle_b32 v94, v240 offset:120
	ds_swizzle_b32 v95, v241 offset:120
	ds_swizzle_b32 v72, v240 offset:152
	ds_swizzle_b32 v73, v241 offset:152
	ds_swizzle_b32 v74, v240 offset:184
	ds_swizzle_b32 v75, v241 offset:184
	ds_swizzle_b32 v68, v240 offset:216
	ds_swizzle_b32 v69, v241 offset:216
	ds_swizzle_b32 v70, v240 offset:248
	ds_swizzle_b32 v71, v241 offset:248
	s_waitcnt lgkmcnt(14)
	s_nop 0
	v_lshl_add_u32 v1, v108, 7, v0
	s_add_u32 s9, s30, s24
	v_lshl_add_u32 v2, v109, 7, v0
	global_load_dwordx4 v[64:67], v1, s[4:5]
	global_load_dwordx4 v[60:63], v2, s[4:5]
	s_waitcnt lgkmcnt(12)
	v_lshl_add_u32 v1, v110, 7, v0
	s_addc_u32 s11, s31, s25
	s_lshl_b64 s[16:17], s[16:17], 2
	v_lshl_add_u32 v2, v111, 7, v0
	global_load_dwordx4 v[56:59], v1, s[4:5]
	global_load_dwordx4 v[52:55], v2, s[4:5]
	s_waitcnt lgkmcnt(10)
	v_lshl_add_u32 v1, v92, 7, v0
	s_add_u32 s16, s9, s16
	v_lshl_add_u32 v2, v93, 7, v0
	global_load_dwordx4 v[48:51], v1, s[4:5]
	global_load_dwordx4 v[44:47], v2, s[4:5]
	s_waitcnt lgkmcnt(8)
	v_lshl_add_u32 v1, v94, 7, v0
	s_addc_u32 s17, s11, s17
	v_lshl_add_u32 v2, v95, 7, v0
	global_load_dwordx4 v[40:43], v1, s[4:5]
	global_load_dwordx4 v[36:39], v2, s[4:5]
	s_waitcnt lgkmcnt(6)
	v_lshl_add_u32 v1, v72, 7, v0
	s_cmp_lt_i32 s22, 8
	v_lshl_add_u32 v2, v73, 7, v0
	global_load_dwordx4 v[32:35], v1, s[4:5]
	global_load_dwordx4 v[28:31], v2, s[4:5]
	s_waitcnt lgkmcnt(4)
	v_lshl_add_u32 v1, v74, 7, v0
	s_cselect_b32 s24, s23, s8
	v_lshl_add_u32 v2, v75, 7, v0
	global_load_dwordx4 v[24:27], v1, s[4:5]
	global_load_dwordx4 v[20:23], v2, s[4:5]
	s_waitcnt lgkmcnt(2)
	s_nop 0
	v_lshl_add_u32 v1, v68, 7, v0
	s_ashr_i32 s25, s24, 31
	v_lshl_add_u32 v2, v69, 7, v0
	global_load_dwordx4 v[16:19], v1, s[4:5]
	global_load_dwordx4 v[12:15], v2, s[4:5]
	s_waitcnt lgkmcnt(0)
	v_lshl_add_u32 v1, v70, 7, v0
	v_lshl_add_u32 v0, v71, 7, v0
	s_lshl_b64 s[24:25], s[24:25], 9
	global_load_dwordx4 v[4:7], v1, s[4:5]
	global_load_dwordx4 v[8:11], v0, s[4:5]
	v_lshl_add_u64 v[0:1], s[26:27], 0, v[154:155]
	s_add_u32 s98, s20, s24
	s_addc_u32 s99, s21, s25
	global_load_dword v158, v155, s[16:17]
	global_load_dwordx2 v[240:241], v243, s[98:99]
	s_nop 0
	global_load_dwordx4 v[0:3], v[0:1], off
	s_nop 0
	v_mov_b32_e32 v153, 0
	v_dot4c_i32_i8_e32 v153, v148, v104
	v_mov_b32_e32 v148, 0
	v_dot4c_i32_i8_e32 v148, v144, v104
	v_dot4c_i32_i8_e32 v148, v145, v105
	v_dot4c_i32_i8_e32 v148, v146, v106
	v_dot4c_i32_i8_e32 v148, v147, v107
	v_dot4c_i32_i8_e32 v153, v149, v105
	v_dot4c_i32_i8_e32 v153, v150, v106
	v_dot4c_i32_i8_e32 v153, v151, v107
	v_add_u32_dpp v144, v148, v148 quad_perm:[1,0,3,2] row_mask:0xf bank_mask:0xf bound_ctrl:1
	v_mov_b32_e32 v148, 0
	v_dot4c_i32_i8_e32 v148, v140, v104
	v_mov_b32_e32 v140, 0
	v_dot4c_i32_i8_e32 v140, v136, v104
	v_dot4c_i32_i8_e32 v140, v137, v105
	v_dot4c_i32_i8_e32 v140, v138, v106
	v_dot4c_i32_i8_e32 v140, v139, v107
	v_dot4c_i32_i8_e32 v148, v141, v105
	v_dot4c_i32_i8_e32 v148, v142, v106
	v_dot4c_i32_i8_e32 v148, v143, v107
	v_add_u32_dpp v136, v140, v140 quad_perm:[1,0,3,2] row_mask:0xf bank_mask:0xf bound_ctrl:1
	v_mov_b32_e32 v140, 0
	v_dot4c_i32_i8_e32 v140, v132, v104
	v_mov_b32_e32 v132, 0
	v_dot4c_i32_i8_e32 v132, v128, v104
	v_dot4c_i32_i8_e32 v132, v129, v105
	v_dot4c_i32_i8_e32 v132, v130, v106
	v_dot4c_i32_i8_e32 v132, v131, v107
	v_dot4c_i32_i8_e32 v140, v133, v105
	v_dot4c_i32_i8_e32 v140, v134, v106
	v_dot4c_i32_i8_e32 v140, v135, v107
	v_add_u32_dpp v128, v132, v132 quad_perm:[1,0,3,2] row_mask:0xf bank_mask:0xf bound_ctrl:1
	v_mov_b32_e32 v132, 0
	v_dot4c_i32_i8_e32 v132, v124, v104
	v_mov_b32_e32 v124, 0
	v_dot4c_i32_i8_e32 v124, v120, v104
	v_dot4c_i32_i8_e32 v124, v121, v105
	v_dot4c_i32_i8_e32 v124, v122, v106
	v_dot4c_i32_i8_e32 v124, v123, v107
	v_dot4c_i32_i8_e32 v132, v125, v105
	v_dot4c_i32_i8_e32 v132, v126, v106
	v_dot4c_i32_i8_e32 v132, v127, v107
	v_add_u32_dpp v120, v124, v124 quad_perm:[1,0,3,2] row_mask:0xf bank_mask:0xf bound_ctrl:1
	v_mov_b32_e32 v124, 0
	v_dot4c_i32_i8_e32 v124, v116, v104
	v_mov_b32_e32 v116, 0
	v_dot4c_i32_i8_e32 v116, v112, v104
	v_dot4c_i32_i8_e32 v116, v113, v105
	v_dot4c_i32_i8_e32 v116, v114, v106
	v_dot4c_i32_i8_e32 v116, v115, v107
	v_dot4c_i32_i8_e32 v124, v117, v105
	v_dot4c_i32_i8_e32 v124, v118, v106
	v_dot4c_i32_i8_e32 v124, v119, v107
	v_add_u32_dpp v112, v116, v116 quad_perm:[1,0,3,2] row_mask:0xf bank_mask:0xf bound_ctrl:1
	v_mov_b32_e32 v116, 0
	v_dot4c_i32_i8_e32 v116, v100, v104
	v_mov_b32_e32 v100, 0
	v_dot4c_i32_i8_e32 v100, v96, v104
	v_dot4c_i32_i8_e32 v100, v97, v105
	v_dot4c_i32_i8_e32 v100, v98, v106
	v_dot4c_i32_i8_e32 v100, v99, v107
	v_dot4c_i32_i8_e32 v116, v101, v105
	v_dot4c_i32_i8_e32 v116, v102, v106
	v_dot4c_i32_i8_e32 v116, v103, v107
	v_add_u32_dpp v96, v100, v100 quad_perm:[1,0,3,2] row_mask:0xf bank_mask:0xf bound_ctrl:1
	v_mov_b32_e32 v100, 0
	v_dot4c_i32_i8_e32 v100, v88, v104
	v_mov_b32_e32 v88, 0
	v_dot4c_i32_i8_e32 v88, v84, v104
	v_dot4c_i32_i8_e32 v88, v85, v105
	v_dot4c_i32_i8_e32 v88, v86, v106
	v_dot4c_i32_i8_e32 v88, v87, v107
	v_dot4c_i32_i8_e32 v100, v89, v105
	v_dot4c_i32_i8_e32 v100, v90, v106
	v_dot4c_i32_i8_e32 v100, v91, v107
	v_add_u32_dpp v84, v88, v88 quad_perm:[1,0,3,2] row_mask:0xf bank_mask:0xf bound_ctrl:1
	v_mov_b32_e32 v88, 0
	v_dot4c_i32_i8_e32 v88, v80, v104
	v_mov_b32_e32 v80, 0
	v_dot4c_i32_i8_e32 v80, v76, v104
	v_dot4c_i32_i8_e32 v88, v81, v105
	v_dot4c_i32_i8_e32 v80, v77, v105
	v_dot4c_i32_i8_e32 v88, v82, v106
	v_dot4c_i32_i8_e32 v80, v78, v106
	v_dot4c_i32_i8_e32 v88, v83, v107
	v_dot4c_i32_i8_e32 v80, v79, v107
	v_add_u32_dpp v145, v153, v153 quad_perm:[1,0,3,2] row_mask:0xf bank_mask:0xf bound_ctrl:1
	v_add_u32_dpp v137, v148, v148 quad_perm:[1,0,3,2] row_mask:0xf bank_mask:0xf bound_ctrl:1
	v_add_u32_dpp v129, v140, v140 quad_perm:[1,0,3,2] row_mask:0xf bank_mask:0xf bound_ctrl:1
	v_add_u32_dpp v121, v132, v132 quad_perm:[1,0,3,2] row_mask:0xf bank_mask:0xf bound_ctrl:1
	v_add_u32_dpp v113, v124, v124 quad_perm:[1,0,3,2] row_mask:0xf bank_mask:0xf bound_ctrl:1
	v_add_u32_dpp v97, v116, v116 quad_perm:[1,0,3,2] row_mask:0xf bank_mask:0xf bound_ctrl:1
	v_add_u32_dpp v85, v100, v100 quad_perm:[1,0,3,2] row_mask:0xf bank_mask:0xf bound_ctrl:1
	v_add_u32_dpp v76, v80, v80 quad_perm:[1,0,3,2] row_mask:0xf bank_mask:0xf bound_ctrl:1
	v_add_u32_dpp v77, v88, v88 quad_perm:[1,0,3,2] row_mask:0xf bank_mask:0xf bound_ctrl:1
	v_add_u32_dpp v144, v144, v144 quad_perm:[2,3,0,1] row_mask:0xf bank_mask:0xf bound_ctrl:1
	v_add_u32_dpp v145, v145, v145 quad_perm:[2,3,0,1] row_mask:0xf bank_mask:0xf bound_ctrl:1
	v_add_u32_dpp v136, v136, v136 quad_perm:[2,3,0,1] row_mask:0xf bank_mask:0xf bound_ctrl:1
	v_add_u32_dpp v137, v137, v137 quad_perm:[2,3,0,1] row_mask:0xf bank_mask:0xf bound_ctrl:1
	v_add_u32_dpp v128, v128, v128 quad_perm:[2,3,0,1] row_mask:0xf bank_mask:0xf bound_ctrl:1
	v_add_u32_dpp v130, v129, v129 quad_perm:[2,3,0,1] row_mask:0xf bank_mask:0xf bound_ctrl:1
	v_add_u32_dpp v120, v120, v120 quad_perm:[2,3,0,1] row_mask:0xf bank_mask:0xf bound_ctrl:1
	v_add_u32_dpp v121, v121, v121 quad_perm:[2,3,0,1] row_mask:0xf bank_mask:0xf bound_ctrl:1
	v_add_u32_dpp v112, v112, v112 quad_perm:[2,3,0,1] row_mask:0xf bank_mask:0xf bound_ctrl:1
	v_add_u32_dpp v113, v113, v113 quad_perm:[2,3,0,1] row_mask:0xf bank_mask:0xf bound_ctrl:1
	v_add_u32_dpp v96, v96, v96 quad_perm:[2,3,0,1] row_mask:0xf bank_mask:0xf bound_ctrl:1
	v_add_u32_dpp v97, v97, v97 quad_perm:[2,3,0,1] row_mask:0xf bank_mask:0xf bound_ctrl:1
	v_add_u32_dpp v84, v84, v84 quad_perm:[2,3,0,1] row_mask:0xf bank_mask:0xf bound_ctrl:1
	v_add_u32_dpp v85, v85, v85 quad_perm:[2,3,0,1] row_mask:0xf bank_mask:0xf bound_ctrl:1
	v_add_u32_dpp v76, v76, v76 quad_perm:[2,3,0,1] row_mask:0xf bank_mask:0xf bound_ctrl:1
	v_add_u32_dpp v77, v77, v77 quad_perm:[2,3,0,1] row_mask:0xf bank_mask:0xf bound_ctrl:1
	v_mov_b32_dpp v146, v145 row_half_mirror row_mask:0xf bank_mask:0xf bound_ctrl:1
	v_mov_b32_dpp v147, v144 row_half_mirror row_mask:0xf bank_mask:0xf bound_ctrl:1
	v_mov_b32_dpp v138, v137 row_half_mirror row_mask:0xf bank_mask:0xf bound_ctrl:1
	v_mov_b32_dpp v139, v136 row_half_mirror row_mask:0xf bank_mask:0xf bound_ctrl:1
	v_mov_b32_dpp v131, v130 row_half_mirror row_mask:0xf bank_mask:0xf bound_ctrl:1
	v_mov_b32_dpp v129, v128 row_half_mirror row_mask:0xf bank_mask:0xf bound_ctrl:1
	v_mov_b32_dpp v122, v121 row_half_mirror row_mask:0xf bank_mask:0xf bound_ctrl:1
	v_mov_b32_dpp v123, v120 row_half_mirror row_mask:0xf bank_mask:0xf bound_ctrl:1
	v_mov_b32_dpp v114, v113 row_half_mirror row_mask:0xf bank_mask:0xf bound_ctrl:1
	v_mov_b32_dpp v115, v112 row_half_mirror row_mask:0xf bank_mask:0xf bound_ctrl:1
	v_mov_b32_dpp v98, v97 row_half_mirror row_mask:0xf bank_mask:0xf bound_ctrl:1
	v_mov_b32_dpp v99, v96 row_half_mirror row_mask:0xf bank_mask:0xf bound_ctrl:1
	v_mov_b32_dpp v86, v85 row_half_mirror row_mask:0xf bank_mask:0xf bound_ctrl:1
	v_mov_b32_dpp v87, v84 row_half_mirror row_mask:0xf bank_mask:0xf bound_ctrl:1
	v_mov_b32_dpp v78, v77 row_half_mirror row_mask:0xf bank_mask:0xf bound_ctrl:1
	v_mov_b32_dpp v79, v76 row_half_mirror row_mask:0xf bank_mask:0xf bound_ctrl:1
	s_and_saveexec_b64 s[16:17], s[2:3]
	s_cbranch_execz .LBB0_534
	v_add_u32_e32 v88, v77, v78
	v_add_u32_e32 v89, v76, v79
	v_add_u32_e32 v78, v137, v138
	v_add_u32_e32 v79, v136, v139
	v_add_u32_e32 v76, v145, v146
	v_add_u32_e32 v77, v144, v147
	v_add_u32_e32 v82, v121, v122
	v_add_u32_e32 v83, v120, v123
	v_add_u32_e32 v80, v130, v131
	v_cvt_f32_i32_e32 v77, v77
	v_cvt_f32_i32_e32 v76, v76
	v_cvt_f32_i32_e32 v79, v79
	v_cvt_f32_i32_e32 v78, v78
	v_add_u32_e32 v81, v128, v129
	v_cvt_f32_i32_e32 v81, v81
	v_cvt_f32_i32_e32 v80, v80
	v_cvt_f32_i32_e32 v83, v83
	v_cvt_f32_i32_e32 v82, v82
	v_add_u32_e32 v86, v85, v86
	v_add_u32_e32 v87, v84, v87
	v_add_u32_e32 v84, v97, v98
	v_add_u32_e32 v85, v96, v99
	v_add_u32_e32 v90, v113, v114
	v_add_u32_e32 v91, v112, v115
	v_pk_mul_f32 v[76:77], v[160:161], v[76:77] op_sel_hi:[0,1]
	v_pk_mul_f32 v[78:79], v[160:161], v[78:79] op_sel_hi:[0,1]
	v_cvt_pk_f16_f32 v76, v76, v77
	v_cvt_pk_f16_f32 v77, v78, v79
	v_pk_mul_f32 v[78:79], v[160:161], v[80:81] op_sel_hi:[0,1]
	v_pk_mul_f32 v[80:81], v[160:161], v[82:83] op_sel_hi:[0,1]
	v_cvt_f32_i32_e32 v83, v91
	v_cvt_f32_i32_e32 v82, v90
	v_cvt_f32_i32_e32 v85, v85
	v_cvt_f32_i32_e32 v84, v84
	v_cvt_pk_f16_f32 v78, v78, v79
	v_cvt_pk_f16_f32 v79, v80, v81
	v_pk_mul_f32 v[80:81], v[160:161], v[82:83] op_sel_hi:[0,1]
	v_pk_mul_f32 v[82:83], v[160:161], v[84:85] op_sel_hi:[0,1]
	v_cvt_f32_i32_e32 v85, v87
	v_cvt_f32_i32_e32 v84, v86
	v_cvt_f32_i32_e32 v87, v89
	v_cvt_f32_i32_e32 v86, v88
	s_ashr_i32 s11, s10, 31
	s_ashr_i32 s9, s8, 31
	s_lshl_b64 s[10:11], s[10:11], 22
	s_add_u32 s10, s14, s10
	s_addc_u32 s11, s15, s11
	s_lshl_b64 s[8:9], s[8:9], 8
	v_cvt_pk_f16_f32 v80, v80, v81
	v_cvt_pk_f16_f32 v81, v82, v83
	v_pk_mul_f32 v[82:83], v[160:161], v[84:85] op_sel_hi:[0,1]
	v_pk_mul_f32 v[84:85], v[160:161], v[86:87] op_sel_hi:[0,1]
	s_add_u32 s8, s10, s8
	v_cvt_pk_f16_f32 v82, v82, v83
	v_cvt_pk_f16_f32 v83, v84, v85
	s_addc_u32 s9, s11, s9
	v_lshlrev_b32_e32 v84, 1, v152
	global_store_dwordx4 v84, v[76:79], s[8:9]
	global_store_dwordx4 v84, v[80:83], s[8:9] offset:16
	s_branch .LBB0_534

.LBB0_622:
	s_mov_b32 s9, s18
	s_cmp_lt_i32 s22, 8
	s_cselect_b32 s17, s22, s9
	s_waitcnt vmcnt(1)
	ds_swizzle_b32 v140, v250 offset:24
	ds_swizzle_b32 v141, v251 offset:24
	ds_swizzle_b32 v142, v250 offset:56
	ds_swizzle_b32 v143, v251 offset:56
	ds_swizzle_b32 v132, v250 offset:88
	ds_swizzle_b32 v133, v251 offset:88
	ds_swizzle_b32 v134, v250 offset:120
	ds_swizzle_b32 v135, v251 offset:120
	ds_swizzle_b32 v108, v250 offset:152
	ds_swizzle_b32 v109, v251 offset:152
	ds_swizzle_b32 v110, v250 offset:184
	ds_swizzle_b32 v111, v251 offset:184
	ds_swizzle_b32 v100, v250 offset:216
	ds_swizzle_b32 v101, v251 offset:216
	ds_swizzle_b32 v102, v250 offset:248
	ds_swizzle_b32 v103, v251 offset:248
	s_waitcnt lgkmcnt(14)
	s_nop 0
	v_lshl_or_b32 v80, s17, 21, v196
	s_waitcnt vmcnt(1)
	v_lshl_add_u32 v81, v140, 7, v80
	v_lshl_add_u32 v82, v141, 7, v80
	s_mov_b32 s16, s23
	global_load_dwordx4 v[168:171], v81, s[4:5]
	global_load_dwordx4 v[164:167], v82, s[4:5]
	s_waitcnt lgkmcnt(12)
	v_lshl_add_u32 v81, v142, 7, v80
	v_lshl_add_u32 v82, v143, 7, v80
	global_load_dwordx4 v[160:163], v81, s[4:5]
	global_load_dwordx4 v[156:159], v82, s[4:5]
	s_waitcnt lgkmcnt(10)
	v_lshl_add_u32 v81, v132, 7, v80
	v_lshl_add_u32 v82, v133, 7, v80
	s_cselect_b32 s20, s8, s16
	global_load_dwordx4 v[152:155], v81, s[4:5]
	global_load_dwordx4 v[144:147], v82, s[4:5]
	s_waitcnt lgkmcnt(8)
	v_lshl_add_u32 v81, v134, 7, v80
	v_lshl_add_u32 v82, v135, 7, v80
	s_ashr_i32 s21, s20, 31
	global_load_dwordx4 v[136:139], v81, s[4:5]
	global_load_dwordx4 v[128:131], v82, s[4:5]
	s_waitcnt lgkmcnt(6)
	v_lshl_add_u32 v81, v108, 7, v80
	v_lshl_add_u32 v82, v109, 7, v80
	s_lshl_b64 s[20:21], s[20:21], 9
	global_load_dwordx4 v[124:127], v81, s[4:5]
	global_load_dwordx4 v[120:123], v82, s[4:5]
	s_waitcnt lgkmcnt(4)
	v_lshl_add_u32 v81, v110, 7, v80
	v_lshl_add_u32 v82, v111, 7, v80
	s_cmp_lt_i32 s27, 8
	global_load_dwordx4 v[112:115], v81, s[4:5]
	global_load_dwordx4 v[104:107], v82, s[4:5]
	s_waitcnt lgkmcnt(2)
	s_nop 0
	v_lshl_add_u32 v81, v100, 7, v80
	v_lshl_add_u32 v82, v101, 7, v80
	v_lshl_add_u64 v[100:101], v[244:245], 0, s[20:21]
	s_cselect_b64 s[20:21], -1, 0
	s_and_b64 s[24:25], s[20:21], exec
	s_cselect_b32 s24, s26, s16
	s_ashr_i32 s25, s24, 31
	global_load_dwordx4 v[96:99], v81, s[4:5]
	global_load_dwordx4 v[92:95], v82, s[4:5]
	s_waitcnt lgkmcnt(0)
	v_lshl_add_u32 v81, v102, 7, v80
	v_lshl_add_u32 v80, v103, 7, v80
	s_lshl_b64 s[24:25], s[24:25], 9
	global_load_dwordx4 v[88:91], v81, s[4:5]
	s_nop 0
	global_load_dwordx4 v[80:83], v80, s[4:5]
	s_nop 0
	ds_swizzle_b32 v60, v248 offset:24
	ds_swizzle_b32 v61, v249 offset:24
	ds_swizzle_b32 v62, v248 offset:56
	ds_swizzle_b32 v63, v249 offset:56
	ds_swizzle_b32 v36, v248 offset:88
	ds_swizzle_b32 v37, v249 offset:88
	ds_swizzle_b32 v38, v248 offset:120
	ds_swizzle_b32 v39, v249 offset:120
	ds_swizzle_b32 v12, v248 offset:152
	ds_swizzle_b32 v13, v249 offset:152
	ds_swizzle_b32 v14, v248 offset:184
	ds_swizzle_b32 v15, v249 offset:184
	ds_swizzle_b32 v0, v248 offset:216
	ds_swizzle_b32 v1, v249 offset:216
	ds_swizzle_b32 v2, v248 offset:248
	ds_swizzle_b32 v3, v249 offset:248
	global_load_dwordx2 v[248:249], v[100:101], off
	v_lshl_add_u64 v[100:101], v[246:247], 0, s[24:25]
	global_load_dwordx2 v[250:251], v[100:101], off
	s_waitcnt lgkmcnt(0)
	s_nop 0
	v_cvt_scalef32_pk_f16_fp8 v100, v76, 1.0
	v_cvt_scalef32_pk_f16_fp8 v76, v76, 1.0 op_sel:[1,0,0]
	v_cvt_scalef32_pk_f16_fp8 v101, v77, 1.0
	v_cvt_scalef32_pk_f16_fp8 v77, v77, 1.0 op_sel:[1,0,0]
	v_cvt_scalef32_pk_f16_fp8 v102, v78, 1.0
	v_cvt_scalef32_pk_f16_fp8 v78, v78, 1.0 op_sel:[1,0,0]
	v_cvt_scalef32_pk_f16_fp8 v103, v79, 1.0
	v_cvt_scalef32_pk_f16_fp8 v79, v79, 1.0 op_sel:[1,0,0]
	v_pk_fma_f16 v100, v100, v60, 0
	v_pk_fma_f16 v76, v76, v60, 0
	v_pk_fma_f16 v101, v101, v60, 0
	v_pk_fma_f16 v77, v77, v60, 0
	v_pk_fma_f16 v102, v102, v60, 0
	v_pk_fma_f16 v78, v78, v60, 0
	v_pk_fma_f16 v103, v103, v60, 0
	v_pk_fma_f16 v60, v79, v60, 0
	v_cvt_scalef32_pk_f16_fp8 v79, v72, 1.0
	v_cvt_scalef32_pk_f16_fp8 v72, v72, 1.0 op_sel:[1,0,0]
	v_pk_fma_f16 v72, v72, v61, v76
	v_cvt_scalef32_pk_f16_fp8 v76, v73, 1.0
	v_cvt_scalef32_pk_f16_fp8 v73, v73, 1.0 op_sel:[1,0,0]
	v_pk_fma_f16 v73, v73, v61, v77
	v_cvt_scalef32_pk_f16_fp8 v77, v74, 1.0
	v_cvt_scalef32_pk_f16_fp8 v74, v74, 1.0 op_sel:[1,0,0]
	v_pk_fma_f16 v74, v74, v61, v78
	v_cvt_scalef32_pk_f16_fp8 v78, v75, 1.0
	v_cvt_scalef32_pk_f16_fp8 v75, v75, 1.0 op_sel:[1,0,0]
	v_pk_fma_f16 v79, v79, v61, v100
	v_pk_fma_f16 v76, v76, v61, v101
	v_pk_fma_f16 v77, v77, v61, v102
	v_pk_fma_f16 v78, v78, v61, v103
	v_pk_fma_f16 v60, v75, v61, v60
	v_cvt_scalef32_pk_f16_fp8 v61, v68, 1.0
	v_cvt_scalef32_pk_f16_fp8 v68, v68, 1.0 op_sel:[1,0,0]
	v_pk_fma_f16 v68, v68, v62, v72
	v_cvt_scalef32_pk_f16_fp8 v72, v69, 1.0
	v_cvt_scalef32_pk_f16_fp8 v69, v69, 1.0 op_sel:[1,0,0]
	v_pk_fma_f16 v69, v69, v62, v73
	v_cvt_scalef32_pk_f16_fp8 v73, v70, 1.0
	v_cvt_scalef32_pk_f16_fp8 v70, v70, 1.0 op_sel:[1,0,0]
	v_pk_fma_f16 v70, v70, v62, v74
	v_cvt_scalef32_pk_f16_fp8 v74, v71, 1.0
	v_cvt_scalef32_pk_f16_fp8 v71, v71, 1.0 op_sel:[1,0,0]
	v_pk_fma_f16 v61, v61, v62, v79
	v_pk_fma_f16 v72, v72, v62, v76
	v_pk_fma_f16 v73, v73, v62, v77
	v_pk_fma_f16 v74, v74, v62, v78
	v_pk_fma_f16 v60, v71, v62, v60
	v_cvt_scalef32_pk_f16_fp8 v62, v64, 1.0
	v_pk_fma_f16 v61, v62, v63, v61
	v_cvt_scalef32_pk_f16_fp8 v62, v64, 1.0 op_sel:[1,0,0]
	v_cvt_scalef32_pk_f16_fp8 v64, v65, 1.0
	v_cvt_scalef32_pk_f16_fp8 v65, v65, 1.0 op_sel:[1,0,0]
	v_pk_fma_f16 v62, v62, v63, v68
	v_pk_fma_f16 v65, v65, v63, v69
	v_cvt_scalef32_pk_f16_fp8 v68, v66, 1.0
	v_cvt_scalef32_pk_f16_fp8 v66, v66, 1.0 op_sel:[1,0,0]
	v_cvt_scalef32_pk_f16_fp8 v69, v67, 1.0
	v_cvt_scalef32_pk_f16_fp8 v67, v67, 1.0 op_sel:[1,0,0]
	v_pk_fma_f16 v64, v64, v63, v72
	v_pk_fma_f16 v68, v68, v63, v73
	v_pk_fma_f16 v66, v66, v63, v70
	v_pk_fma_f16 v69, v69, v63, v74
	v_pk_fma_f16 v60, v67, v63, v60
	v_cvt_scalef32_pk_f16_fp8 v63, v56, 1.0
	v_cvt_scalef32_pk_f16_fp8 v56, v56, 1.0 op_sel:[1,0,0]
	v_pk_fma_f16 v56, v56, v36, v62
	v_cvt_scalef32_pk_f16_fp8 v62, v57, 1.0
	v_pk_fma_f16 v61, v63, v36, v61
	v_pk_fma_f16 v62, v62, v36, v64
	v_cvt_scalef32_pk_f16_fp8 v57, v57, 1.0 op_sel:[1,0,0]
	v_cvt_scalef32_pk_f16_fp8 v63, v58, 1.0
	v_cvt_scalef32_pk_f16_fp8 v58, v58, 1.0 op_sel:[1,0,0]
	v_cvt_scalef32_pk_f16_fp8 v64, v59, 1.0
	v_cvt_scalef32_pk_f16_fp8 v59, v59, 1.0 op_sel:[1,0,0]
	v_pk_fma_f16 v57, v57, v36, v65
	v_pk_fma_f16 v63, v63, v36, v68
	v_pk_fma_f16 v58, v58, v36, v66
	v_pk_fma_f16 v64, v64, v36, v69
	v_pk_fma_f16 v36, v59, v36, v60
	v_cvt_scalef32_pk_f16_fp8 v59, v52, 1.0
	v_cvt_scalef32_pk_f16_fp8 v52, v52, 1.0 op_sel:[1,0,0]
	v_pk_fma_f16 v52, v52, v37, v56
	v_cvt_scalef32_pk_f16_fp8 v56, v53, 1.0
	v_cvt_scalef32_pk_f16_fp8 v53, v53, 1.0 op_sel:[1,0,0]
	v_pk_fma_f16 v53, v53, v37, v57
	v_cvt_scalef32_pk_f16_fp8 v57, v54, 1.0
	v_cvt_scalef32_pk_f16_fp8 v54, v54, 1.0 op_sel:[1,0,0]
	v_pk_fma_f16 v54, v54, v37, v58
	v_cvt_scalef32_pk_f16_fp8 v58, v55, 1.0
	v_cvt_scalef32_pk_f16_fp8 v55, v55, 1.0 op_sel:[1,0,0]
	v_pk_fma_f16 v59, v59, v37, v61
	v_pk_fma_f16 v56, v56, v37, v62
	v_pk_fma_f16 v57, v57, v37, v63
	v_pk_fma_f16 v58, v58, v37, v64
	v_pk_fma_f16 v36, v55, v37, v36
	v_cvt_scalef32_pk_f16_fp8 v37, v48, 1.0
	v_cvt_scalef32_pk_f16_fp8 v48, v48, 1.0 op_sel:[1,0,0]
	v_pk_fma_f16 v48, v48, v38, v52
	v_cvt_scalef32_pk_f16_fp8 v52, v49, 1.0
	v_cvt_scalef32_pk_f16_fp8 v49, v49, 1.0 op_sel:[1,0,0]
	v_pk_fma_f16 v49, v49, v38, v53
	v_cvt_scalef32_pk_f16_fp8 v53, v50, 1.0
	v_cvt_scalef32_pk_f16_fp8 v50, v50, 1.0 op_sel:[1,0,0]
	v_pk_fma_f16 v50, v50, v38, v54
	v_cvt_scalef32_pk_f16_fp8 v54, v51, 1.0
	v_cvt_scalef32_pk_f16_fp8 v51, v51, 1.0 op_sel:[1,0,0]
	v_pk_fma_f16 v37, v37, v38, v59
	v_pk_fma_f16 v52, v52, v38, v56
	v_pk_fma_f16 v53, v53, v38, v57
	v_pk_fma_f16 v54, v54, v38, v58
	v_pk_fma_f16 v36, v51, v38, v36
	v_cvt_scalef32_pk_f16_fp8 v38, v44, 1.0
	v_pk_fma_f16 v37, v38, v39, v37
	v_cvt_scalef32_pk_f16_fp8 v38, v44, 1.0 op_sel:[1,0,0]
	v_cvt_scalef32_pk_f16_fp8 v44, v45, 1.0
	v_cvt_scalef32_pk_f16_fp8 v45, v45, 1.0 op_sel:[1,0,0]
	v_pk_fma_f16 v38, v38, v39, v48
	v_pk_fma_f16 v45, v45, v39, v49
	v_cvt_scalef32_pk_f16_fp8 v48, v46, 1.0
	v_cvt_scalef32_pk_f16_fp8 v46, v46, 1.0 op_sel:[1,0,0]
	v_cvt_scalef32_pk_f16_fp8 v49, v47, 1.0
	v_cvt_scalef32_pk_f16_fp8 v47, v47, 1.0 op_sel:[1,0,0]
	v_pk_fma_f16 v44, v44, v39, v52
	v_pk_fma_f16 v48, v48, v39, v53
	v_pk_fma_f16 v46, v46, v39, v50
	v_pk_fma_f16 v49, v49, v39, v54
	v_pk_fma_f16 v36, v47, v39, v36
	v_cvt_scalef32_pk_f16_fp8 v39, v40, 1.0
	v_pk_fma_f16 v37, v39, v12, v37
	v_cvt_scalef32_pk_f16_fp8 v39, v40, 1.0 op_sel:[1,0,0]
	v_pk_fma_f16 v38, v39, v12, v38
	v_cvt_scalef32_pk_f16_fp8 v39, v41, 1.0
	v_pk_fma_f16 v39, v39, v12, v44
	v_cvt_scalef32_pk_f16_fp8 v40, v41, 1.0 op_sel:[1,0,0]
	v_cvt_scalef32_pk_f16_fp8 v41, v42, 1.0
	v_cvt_scalef32_pk_f16_fp8 v42, v42, 1.0 op_sel:[1,0,0]
	v_cvt_scalef32_pk_f16_fp8 v44, v43, 1.0
	v_cvt_scalef32_pk_f16_fp8 v43, v43, 1.0 op_sel:[1,0,0]
	v_pk_fma_f16 v40, v40, v12, v45
	v_pk_fma_f16 v41, v41, v12, v48
	v_pk_fma_f16 v42, v42, v12, v46
	v_pk_fma_f16 v44, v44, v12, v49
	v_pk_fma_f16 v12, v43, v12, v36
	v_cvt_scalef32_pk_f16_fp8 v36, v32, 1.0
	v_pk_fma_f16 v36, v36, v13, v37
	v_cvt_scalef32_pk_f16_fp8 v32, v32, 1.0 op_sel:[1,0,0]
	v_cvt_scalef32_pk_f16_fp8 v37, v33, 1.0
	v_pk_fma_f16 v32, v32, v13, v38
	v_pk_fma_f16 v37, v37, v13, v39
	v_cvt_scalef32_pk_f16_fp8 v33, v33, 1.0 op_sel:[1,0,0]
	v_cvt_scalef32_pk_f16_fp8 v38, v34, 1.0
	v_cvt_scalef32_pk_f16_fp8 v34, v34, 1.0 op_sel:[1,0,0]
	v_cvt_scalef32_pk_f16_fp8 v39, v35, 1.0
	v_cvt_scalef32_pk_f16_fp8 v35, v35, 1.0 op_sel:[1,0,0]
	v_pk_fma_f16 v33, v33, v13, v40
	v_pk_fma_f16 v38, v38, v13, v41
	v_pk_fma_f16 v34, v34, v13, v42
	v_pk_fma_f16 v39, v39, v13, v44
	v_pk_fma_f16 v12, v35, v13, v12
	v_cvt_scalef32_pk_f16_fp8 v13, v28, 1.0
	v_cvt_scalef32_pk_f16_fp8 v28, v28, 1.0 op_sel:[1,0,0]
	v_pk_fma_f16 v28, v28, v14, v32
	v_cvt_scalef32_pk_f16_fp8 v32, v29, 1.0
	v_cvt_scalef32_pk_f16_fp8 v29, v29, 1.0 op_sel:[1,0,0]
	v_pk_fma_f16 v29, v29, v14, v33
	v_cvt_scalef32_pk_f16_fp8 v33, v30, 1.0
	v_cvt_scalef32_pk_f16_fp8 v30, v30, 1.0 op_sel:[1,0,0]
	v_pk_fma_f16 v30, v30, v14, v34
	v_cvt_scalef32_pk_f16_fp8 v34, v31, 1.0
	v_cvt_scalef32_pk_f16_fp8 v31, v31, 1.0 op_sel:[1,0,0]
	v_pk_fma_f16 v13, v13, v14, v36
	v_pk_fma_f16 v32, v32, v14, v37
	v_pk_fma_f16 v33, v33, v14, v38
	v_pk_fma_f16 v34, v34, v14, v39
	v_pk_fma_f16 v12, v31, v14, v12
	v_cvt_scalef32_pk_f16_fp8 v14, v24, 1.0
	v_pk_fma_f16 v13, v14, v15, v13
	v_cvt_scalef32_pk_f16_fp8 v14, v24, 1.0 op_sel:[1,0,0]
	v_cvt_scalef32_pk_f16_fp8 v24, v25, 1.0
	v_cvt_scalef32_pk_f16_fp8 v25, v25, 1.0 op_sel:[1,0,0]
	v_pk_fma_f16 v14, v14, v15, v28
	v_pk_fma_f16 v25, v25, v15, v29
	v_cvt_scalef32_pk_f16_fp8 v28, v26, 1.0
	v_cvt_scalef32_pk_f16_fp8 v26, v26, 1.0 op_sel:[1,0,0]
	v_cvt_scalef32_pk_f16_fp8 v29, v27, 1.0
	v_cvt_scalef32_pk_f16_fp8 v27, v27, 1.0 op_sel:[1,0,0]
	v_pk_fma_f16 v24, v24, v15, v32
	v_pk_fma_f16 v28, v28, v15, v33
	v_pk_fma_f16 v26, v26, v15, v30
	v_pk_fma_f16 v29, v29, v15, v34
	v_pk_fma_f16 v12, v27, v15, v12
	v_cvt_scalef32_pk_f16_fp8 v15, v20, 1.0
	v_pk_fma_f16 v13, v15, v0, v13
	v_cvt_scalef32_pk_f16_fp8 v15, v20, 1.0 op_sel:[1,0,0]
	v_pk_fma_f16 v14, v15, v0, v14
	v_cvt_scalef32_pk_f16_fp8 v15, v21, 1.0
	v_pk_fma_f16 v15, v15, v0, v24
	v_cvt_scalef32_pk_f16_fp8 v20, v21, 1.0 op_sel:[1,0,0]
	v_cvt_scalef32_pk_f16_fp8 v21, v22, 1.0
	v_cvt_scalef32_pk_f16_fp8 v22, v22, 1.0 op_sel:[1,0,0]
	v_cvt_scalef32_pk_f16_fp8 v24, v23, 1.0
	v_cvt_scalef32_pk_f16_fp8 v23, v23, 1.0 op_sel:[1,0,0]
	v_pk_fma_f16 v20, v20, v0, v25
	v_pk_fma_f16 v21, v21, v0, v28
	v_pk_fma_f16 v22, v22, v0, v26
	v_pk_fma_f16 v24, v24, v0, v29
	v_pk_fma_f16 v0, v23, v0, v12
	v_cvt_scalef32_pk_f16_fp8 v12, v16, 1.0
	v_pk_fma_f16 v12, v12, v1, v13
	v_cvt_scalef32_pk_f16_fp8 v13, v16, 1.0 op_sel:[1,0,0]
	v_pk_fma_f16 v13, v13, v1, v14
	v_cvt_scalef32_pk_f16_fp8 v14, v17, 1.0
	v_pk_fma_f16 v14, v14, v1, v15
	v_cvt_scalef32_pk_f16_fp8 v15, v17, 1.0 op_sel:[1,0,0]
	v_cvt_scalef32_pk_f16_fp8 v16, v18, 1.0
	v_cvt_scalef32_pk_f16_fp8 v17, v18, 1.0 op_sel:[1,0,0]
	v_cvt_scalef32_pk_f16_fp8 v18, v19, 1.0
	v_cvt_scalef32_pk_f16_fp8 v19, v19, 1.0 op_sel:[1,0,0]
	v_pk_fma_f16 v15, v15, v1, v20
	v_pk_fma_f16 v16, v16, v1, v21
	v_pk_fma_f16 v17, v17, v1, v22
	v_pk_fma_f16 v18, v18, v1, v24
	v_pk_fma_f16 v0, v19, v1, v0
	v_cvt_scalef32_pk_f16_fp8 v1, v4, 1.0
	v_pk_fma_f16 v1, v1, v2, v12
	v_cvt_scalef32_pk_f16_fp8 v4, v4, 1.0 op_sel:[1,0,0]
	v_cvt_scalef32_pk_f16_fp8 v12, v5, 1.0
	v_pk_fma_f16 v4, v4, v2, v13
	v_pk_fma_f16 v12, v12, v2, v14
	v_cvt_scalef32_pk_f16_fp8 v5, v5, 1.0 op_sel:[1,0,0]
	v_cvt_scalef32_pk_f16_fp8 v13, v6, 1.0
	v_cvt_scalef32_pk_f16_fp8 v6, v6, 1.0 op_sel:[1,0,0]
	v_cvt_scalef32_pk_f16_fp8 v14, v7, 1.0
	v_cvt_scalef32_pk_f16_fp8 v7, v7, 1.0 op_sel:[1,0,0]
	v_pk_fma_f16 v5, v5, v2, v15
	v_pk_fma_f16 v13, v13, v2, v16
	v_pk_fma_f16 v6, v6, v2, v17
	v_pk_fma_f16 v14, v14, v2, v18
	v_pk_fma_f16 v0, v7, v2, v0
	v_cvt_scalef32_pk_f16_fp8 v2, v8, 1.0
	v_pk_fma_f16 v1, v2, v3, v1
	v_cvt_scalef32_pk_f16_fp8 v2, v8, 1.0 op_sel:[1,0,0]
	v_cvt_scalef32_pk_f16_fp8 v7, v9, 1.0 op_sel:[1,0,0]
	v_cvt_scalef32_pk_f16_fp8 v8, v10, 1.0 op_sel:[1,0,0]
	v_pk_fma_f16 v2, v2, v3, v4
	v_cvt_scalef32_pk_f16_fp8 v4, v9, 1.0
	v_pk_fma_f16 v5, v7, v3, v5
	v_cvt_scalef32_pk_f16_fp8 v7, v10, 1.0
	v_pk_fma_f16 v6, v8, v3, v6
	v_cvt_scalef32_pk_f16_fp8 v8, v11, 1.0
	v_cvt_scalef32_pk_f16_fp8 v9, v11, 1.0 op_sel:[1,0,0]
	v_pk_fma_f16 v4, v4, v3, v12
	v_pk_fma_f16 v7, v7, v3, v13
	v_pk_fma_f16 v8, v8, v3, v14
	v_pk_fma_f16 v0, v9, v3, v0
	v_permlane32_swap_b32_e32 v1, v7
	v_permlane32_swap_b32_e32 v2, v6
	v_permlane32_swap_b32_e32 v4, v8
	v_permlane32_swap_b32_e32 v5, v0
	v_pk_add_f16 v1, v1, v7
	v_pk_add_f16 v2, v2, v6
	v_pk_add_f16 v3, v4, v8
	v_pk_add_f16 v0, v5, v0
	s_nop 0
	v_permlane16_swap_b32_e32 v1, v3
	v_permlane16_swap_b32_e32 v2, v0
	v_pk_add_f16 v1, v1, v3
	v_pk_add_f16 v0, v2, v0
	s_ashr_i32 s17, s16, 31
	v_cndmask_b32_e64 v2, v1, v0, s[2:3]
	v_cndmask_b32_e64 v0, v0, v1, s[2:3]
	s_lshl_b64 s[16:17], s[16:17], 11
	v_mov_b32_dpp v1, v2 row_ror:8 row_mask:0xf bank_mask:0xf bound_ctrl:1
	v_pk_add_f16 v1, v1, v0
	s_add_u32 s24, s14, s16
	v_cvt_f32_f16_e32 v0, v1
	v_cvt_f32_f16_sdwa v1, v1 dst_sel:DWORD dst_unused:UNUSED_PAD src0_sel:WORD_1
	s_addc_u32 s25, s15, s17
	s_lshl_b32 s16, s9, 7
	s_ashr_i32 s17, s16, 31
	v_pk_mul_f32 v[0:1], v[0:1], s[10:11] op_sel_hi:[1,0]
	s_lshl_b64 s[16:17], s[16:17], 1
	v_and_b32_sdwa v3, v0, v208 dst_sel:DWORD dst_unused:UNUSED_PAD src0_sel:WORD_1 src1_sel:DWORD
	v_and_b32_sdwa v2, v1, v208 dst_sel:DWORD dst_unused:UNUSED_PAD src0_sel:WORD_1 src1_sel:DWORD
	v_add3_u32 v0, v0, v3, s7
	s_add_u32 s16, s24, s16
	v_add3_u32 v1, v1, v2, s7
	v_lshrrev_b32_e32 v0, 16, v0
	s_addc_u32 s17, s25, s17
	v_and_or_b32 v2, v1, s11, v0
	v_lshl_add_u64 v[0:1], s[16:17], 0, v[194:195]
	s_mov_b32 s18, s27
	s_mov_b32 s23, s26
	v_lshl_add_u64 v[0:1], v[0:1], 0, v[204:205]
	s_cmp_gt_i32 s22, 7
	s_mov_b64 s[16:17], -1
	global_store_dword v[0:1], v2, off
	s_cbranch_scc1 .LBB0_621
	s_add_i32 s9, s23, s19
	s_cmpk_gt_i32 s9, 0x3fff
	s_cselect_b32 s25, s33, 0
	s_cselect_b32 s24, s6, s9
	s_add_i32 s25, s25, s18
	s_and_b64 s[16:17], s[20:21], exec
	s_cselect_b32 s9, s18, s22
	v_lshl_or_b32 v0, s9, 21, v196
	s_waitcnt vmcnt(1)
	ds_swizzle_b32 v188, v250 offset:24
	ds_swizzle_b32 v189, v251 offset:24
	ds_swizzle_b32 v190, v250 offset:56
	ds_swizzle_b32 v191, v251 offset:56
	ds_swizzle_b32 v184, v250 offset:88
	ds_swizzle_b32 v185, v251 offset:88
	ds_swizzle_b32 v186, v250 offset:120
	ds_swizzle_b32 v187, v251 offset:120
	ds_swizzle_b32 v180, v250 offset:152
	ds_swizzle_b32 v181, v251 offset:152
	ds_swizzle_b32 v182, v250 offset:184
	ds_swizzle_b32 v183, v251 offset:184
	ds_swizzle_b32 v176, v250 offset:216
	ds_swizzle_b32 v177, v251 offset:216
	ds_swizzle_b32 v178, v250 offset:248
	ds_swizzle_b32 v179, v251 offset:248
	s_waitcnt lgkmcnt(14)
	s_nop 0
	v_lshl_add_u32 v1, v188, 7, v0
	s_cselect_b32 s16, s23, s8
	v_lshl_add_u32 v2, v189, 7, v0
	global_load_dwordx4 v[76:79], v1, s[4:5]
	global_load_dwordx4 v[72:75], v2, s[4:5]
	s_waitcnt lgkmcnt(12)
	v_lshl_add_u32 v1, v190, 7, v0
	s_ashr_i32 s17, s16, 31
	v_lshl_add_u32 v2, v191, 7, v0
	global_load_dwordx4 v[68:71], v1, s[4:5]
	global_load_dwordx4 v[64:67], v2, s[4:5]
	s_waitcnt lgkmcnt(10)
	v_lshl_add_u32 v1, v184, 7, v0
	s_lshl_b64 s[16:17], s[16:17], 9
	v_lshl_add_u32 v2, v185, 7, v0
	global_load_dwordx4 v[56:59], v1, s[4:5]
	global_load_dwordx4 v[52:55], v2, s[4:5]
	s_waitcnt lgkmcnt(8)
	v_lshl_add_u32 v1, v186, 7, v0
	s_cmp_lt_i32 s25, 8
	v_lshl_add_u32 v2, v187, 7, v0
	global_load_dwordx4 v[48:51], v1, s[4:5]
	global_load_dwordx4 v[44:47], v2, s[4:5]
	s_waitcnt lgkmcnt(6)
	v_lshl_add_u32 v1, v180, 7, v0
	v_lshl_add_u64 v[60:61], v[244:245], 0, s[16:17]
	s_cselect_b32 s16, s24, s8
	v_lshl_add_u32 v2, v181, 7, v0
	global_load_dwordx4 v[40:43], v1, s[4:5]
	global_load_dwordx4 v[32:35], v2, s[4:5]
	s_waitcnt lgkmcnt(4)
	v_lshl_add_u32 v1, v182, 7, v0
	s_ashr_i32 s17, s16, 31
	v_lshl_add_u32 v2, v183, 7, v0
	global_load_dwordx4 v[28:31], v1, s[4:5]
	global_load_dwordx4 v[24:27], v2, s[4:5]
	s_waitcnt lgkmcnt(2)
	s_nop 0
	v_lshl_add_u32 v1, v176, 7, v0
	s_lshl_b64 s[16:17], s[16:17], 9
	v_lshl_add_u32 v2, v177, 7, v0
	global_load_dwordx4 v[20:23], v1, s[4:5]
	global_load_dwordx4 v[16:19], v2, s[4:5]
	s_waitcnt lgkmcnt(0)
	v_lshl_add_u32 v1, v178, 7, v0
	v_lshl_add_u32 v0, v179, 7, v0
	v_lshl_add_u64 v[140:141], v[246:247], 0, s[16:17]
	global_load_dwordx4 v[4:7], v1, s[4:5]
	global_load_dwordx4 v[8:11], v0, s[4:5]
	s_nop 0
	ds_swizzle_b32 v172, v248 offset:24
	ds_swizzle_b32 v173, v249 offset:24
	ds_swizzle_b32 v174, v248 offset:56
	ds_swizzle_b32 v175, v249 offset:56
	ds_swizzle_b32 v148, v248 offset:88
	ds_swizzle_b32 v149, v249 offset:88
	ds_swizzle_b32 v150, v248 offset:120
	ds_swizzle_b32 v151, v249 offset:120
	ds_swizzle_b32 v116, v248 offset:152
	ds_swizzle_b32 v117, v249 offset:152
	ds_swizzle_b32 v118, v248 offset:184
	ds_swizzle_b32 v119, v249 offset:184
	ds_swizzle_b32 v84, v248 offset:216
	ds_swizzle_b32 v85, v249 offset:216
	ds_swizzle_b32 v86, v248 offset:248
	ds_swizzle_b32 v87, v249 offset:248
	global_load_dwordx2 v[248:249], v[60:61], off
	s_nop 0
	global_load_dwordx2 v[250:251], v[140:141], off
	s_waitcnt lgkmcnt(0)
	s_nop 0
	v_cvt_scalef32_pk_f16_fp8 v176, v168, 1.0
	v_cvt_scalef32_pk_f16_fp8 v168, v168, 1.0 op_sel:[1,0,0]
	v_cvt_scalef32_pk_f16_fp8 v177, v169, 1.0
	v_cvt_scalef32_pk_f16_fp8 v169, v169, 1.0 op_sel:[1,0,0]
	v_cvt_scalef32_pk_f16_fp8 v178, v170, 1.0
	v_cvt_scalef32_pk_f16_fp8 v170, v170, 1.0 op_sel:[1,0,0]
	v_cvt_scalef32_pk_f16_fp8 v179, v171, 1.0
	v_cvt_scalef32_pk_f16_fp8 v171, v171, 1.0 op_sel:[1,0,0]
	v_pk_fma_f16 v176, v176, v172, 0
	v_pk_fma_f16 v168, v168, v172, 0
	v_pk_fma_f16 v177, v177, v172, 0
	v_pk_fma_f16 v169, v169, v172, 0
	v_pk_fma_f16 v178, v178, v172, 0
	v_pk_fma_f16 v170, v170, v172, 0
	v_pk_fma_f16 v179, v179, v172, 0
	v_pk_fma_f16 v171, v171, v172, 0
	v_cvt_scalef32_pk_f16_fp8 v172, v164, 1.0
	v_cvt_scalef32_pk_f16_fp8 v164, v164, 1.0 op_sel:[1,0,0]
	v_pk_fma_f16 v164, v164, v173, v168
	v_cvt_scalef32_pk_f16_fp8 v168, v165, 1.0
	v_cvt_scalef32_pk_f16_fp8 v165, v165, 1.0 op_sel:[1,0,0]
	v_pk_fma_f16 v165, v165, v173, v169
	v_cvt_scalef32_pk_f16_fp8 v169, v166, 1.0
	v_cvt_scalef32_pk_f16_fp8 v166, v166, 1.0 op_sel:[1,0,0]
	v_pk_fma_f16 v166, v166, v173, v170
	v_cvt_scalef32_pk_f16_fp8 v170, v167, 1.0
	v_cvt_scalef32_pk_f16_fp8 v167, v167, 1.0 op_sel:[1,0,0]
	v_pk_fma_f16 v167, v167, v173, v171
	v_cvt_scalef32_pk_f16_fp8 v171, v160, 1.0
	v_cvt_scalef32_pk_f16_fp8 v160, v160, 1.0 op_sel:[1,0,0]
	v_pk_fma_f16 v160, v160, v174, v164
	v_cvt_scalef32_pk_f16_fp8 v164, v161, 1.0
	v_cvt_scalef32_pk_f16_fp8 v161, v161, 1.0 op_sel:[1,0,0]
	v_pk_fma_f16 v161, v161, v174, v165
	v_cvt_scalef32_pk_f16_fp8 v165, v162, 1.0
	v_cvt_scalef32_pk_f16_fp8 v162, v162, 1.0 op_sel:[1,0,0]
	v_pk_fma_f16 v162, v162, v174, v166
	v_cvt_scalef32_pk_f16_fp8 v166, v163, 1.0
	v_cvt_scalef32_pk_f16_fp8 v163, v163, 1.0 op_sel:[1,0,0]
	v_pk_fma_f16 v163, v163, v174, v167
	v_cvt_scalef32_pk_f16_fp8 v167, v156, 1.0
	v_cvt_scalef32_pk_f16_fp8 v156, v156, 1.0 op_sel:[1,0,0]
	v_pk_fma_f16 v156, v156, v175, v160
	v_cvt_scalef32_pk_f16_fp8 v160, v157, 1.0
	v_cvt_scalef32_pk_f16_fp8 v157, v157, 1.0 op_sel:[1,0,0]
	v_pk_fma_f16 v157, v157, v175, v161
	v_cvt_scalef32_pk_f16_fp8 v161, v158, 1.0
	v_cvt_scalef32_pk_f16_fp8 v158, v158, 1.0 op_sel:[1,0,0]
	v_pk_fma_f16 v158, v158, v175, v162
	v_cvt_scalef32_pk_f16_fp8 v162, v159, 1.0
	v_cvt_scalef32_pk_f16_fp8 v159, v159, 1.0 op_sel:[1,0,0]
	v_pk_fma_f16 v159, v159, v175, v163
	v_cvt_scalef32_pk_f16_fp8 v163, v152, 1.0
	v_cvt_scalef32_pk_f16_fp8 v152, v152, 1.0 op_sel:[1,0,0]
	v_pk_fma_f16 v172, v172, v173, v176
	v_pk_fma_f16 v168, v168, v173, v177
	v_pk_fma_f16 v169, v169, v173, v178
	v_pk_fma_f16 v170, v170, v173, v179
	v_pk_fma_f16 v152, v152, v148, v156
	v_cvt_scalef32_pk_f16_fp8 v156, v153, 1.0
	v_cvt_scalef32_pk_f16_fp8 v153, v153, 1.0 op_sel:[1,0,0]
	v_pk_fma_f16 v171, v171, v174, v172
	v_pk_fma_f16 v164, v164, v174, v168
	v_pk_fma_f16 v165, v165, v174, v169
	v_pk_fma_f16 v166, v166, v174, v170
	v_pk_fma_f16 v153, v153, v148, v157
	v_cvt_scalef32_pk_f16_fp8 v157, v154, 1.0
	v_cvt_scalef32_pk_f16_fp8 v154, v154, 1.0 op_sel:[1,0,0]
	v_pk_fma_f16 v167, v167, v175, v171
	v_pk_fma_f16 v160, v160, v175, v164
	v_pk_fma_f16 v161, v161, v175, v165
	v_pk_fma_f16 v162, v162, v175, v166
	v_pk_fma_f16 v154, v154, v148, v158
	v_cvt_scalef32_pk_f16_fp8 v158, v155, 1.0
	v_cvt_scalef32_pk_f16_fp8 v155, v155, 1.0 op_sel:[1,0,0]
	v_pk_fma_f16 v163, v163, v148, v167
	v_pk_fma_f16 v156, v156, v148, v160
	v_pk_fma_f16 v157, v157, v148, v161
	v_pk_fma_f16 v158, v158, v148, v162
	v_pk_fma_f16 v148, v155, v148, v159
	v_cvt_scalef32_pk_f16_fp8 v155, v144, 1.0
	v_cvt_scalef32_pk_f16_fp8 v144, v144, 1.0 op_sel:[1,0,0]
	v_pk_fma_f16 v144, v144, v149, v152
	v_cvt_scalef32_pk_f16_fp8 v152, v145, 1.0
	v_cvt_scalef32_pk_f16_fp8 v145, v145, 1.0 op_sel:[1,0,0]
	v_pk_fma_f16 v145, v145, v149, v153
	v_cvt_scalef32_pk_f16_fp8 v153, v146, 1.0
	v_cvt_scalef32_pk_f16_fp8 v146, v146, 1.0 op_sel:[1,0,0]
	v_pk_fma_f16 v146, v146, v149, v154
	v_cvt_scalef32_pk_f16_fp8 v154, v147, 1.0
	v_cvt_scalef32_pk_f16_fp8 v147, v147, 1.0 op_sel:[1,0,0]
	v_pk_fma_f16 v147, v147, v149, v148
	v_cvt_scalef32_pk_f16_fp8 v148, v136, 1.0
	v_cvt_scalef32_pk_f16_fp8 v136, v136, 1.0 op_sel:[1,0,0]
	v_pk_fma_f16 v136, v136, v150, v144
	v_cvt_scalef32_pk_f16_fp8 v144, v137, 1.0
	v_cvt_scalef32_pk_f16_fp8 v137, v137, 1.0 op_sel:[1,0,0]
	v_pk_fma_f16 v137, v137, v150, v145
	v_cvt_scalef32_pk_f16_fp8 v145, v138, 1.0
	v_cvt_scalef32_pk_f16_fp8 v138, v138, 1.0 op_sel:[1,0,0]
	v_pk_fma_f16 v138, v138, v150, v146
	v_cvt_scalef32_pk_f16_fp8 v146, v139, 1.0
	v_cvt_scalef32_pk_f16_fp8 v139, v139, 1.0 op_sel:[1,0,0]
	v_pk_fma_f16 v139, v139, v150, v147
	v_cvt_scalef32_pk_f16_fp8 v147, v128, 1.0
	v_cvt_scalef32_pk_f16_fp8 v128, v128, 1.0 op_sel:[1,0,0]
	v_pk_fma_f16 v128, v128, v151, v136
	v_cvt_scalef32_pk_f16_fp8 v136, v129, 1.0
	v_cvt_scalef32_pk_f16_fp8 v129, v129, 1.0 op_sel:[1,0,0]
	v_pk_fma_f16 v129, v129, v151, v137
	v_cvt_scalef32_pk_f16_fp8 v137, v130, 1.0
	v_cvt_scalef32_pk_f16_fp8 v130, v130, 1.0 op_sel:[1,0,0]
	v_pk_fma_f16 v130, v130, v151, v138
	v_cvt_scalef32_pk_f16_fp8 v138, v131, 1.0
	v_cvt_scalef32_pk_f16_fp8 v131, v131, 1.0 op_sel:[1,0,0]
	v_pk_fma_f16 v131, v131, v151, v139
	v_cvt_scalef32_pk_f16_fp8 v139, v124, 1.0
	v_cvt_scalef32_pk_f16_fp8 v124, v124, 1.0 op_sel:[1,0,0]
	v_pk_fma_f16 v155, v155, v149, v163
	v_pk_fma_f16 v152, v152, v149, v156
	v_pk_fma_f16 v153, v153, v149, v157
	v_pk_fma_f16 v154, v154, v149, v158
	v_pk_fma_f16 v124, v124, v116, v128
	v_cvt_scalef32_pk_f16_fp8 v128, v125, 1.0
	v_cvt_scalef32_pk_f16_fp8 v125, v125, 1.0 op_sel:[1,0,0]
	v_pk_fma_f16 v148, v148, v150, v155
	v_pk_fma_f16 v144, v144, v150, v152
	v_pk_fma_f16 v145, v145, v150, v153
	v_pk_fma_f16 v146, v146, v150, v154
	v_pk_fma_f16 v125, v125, v116, v129
	v_cvt_scalef32_pk_f16_fp8 v129, v126, 1.0
	v_cvt_scalef32_pk_f16_fp8 v126, v126, 1.0 op_sel:[1,0,0]
	v_pk_fma_f16 v147, v147, v151, v148
	v_pk_fma_f16 v136, v136, v151, v144
	v_pk_fma_f16 v137, v137, v151, v145
	v_pk_fma_f16 v138, v138, v151, v146
	v_pk_fma_f16 v126, v126, v116, v130
	v_cvt_scalef32_pk_f16_fp8 v130, v127, 1.0
	v_cvt_scalef32_pk_f16_fp8 v127, v127, 1.0 op_sel:[1,0,0]
	v_pk_fma_f16 v139, v139, v116, v147
	v_pk_fma_f16 v128, v128, v116, v136
	v_pk_fma_f16 v129, v129, v116, v137
	v_pk_fma_f16 v130, v130, v116, v138
	v_pk_fma_f16 v116, v127, v116, v131
	v_cvt_scalef32_pk_f16_fp8 v127, v120, 1.0
	v_cvt_scalef32_pk_f16_fp8 v120, v120, 1.0 op_sel:[1,0,0]
	v_pk_fma_f16 v120, v120, v117, v124
	v_cvt_scalef32_pk_f16_fp8 v124, v121, 1.0
	v_cvt_scalef32_pk_f16_fp8 v121, v121, 1.0 op_sel:[1,0,0]
	v_pk_fma_f16 v121, v121, v117, v125
	v_cvt_scalef32_pk_f16_fp8 v125, v122, 1.0
	v_cvt_scalef32_pk_f16_fp8 v122, v122, 1.0 op_sel:[1,0,0]
	v_pk_fma_f16 v122, v122, v117, v126
	v_cvt_scalef32_pk_f16_fp8 v126, v123, 1.0
	v_cvt_scalef32_pk_f16_fp8 v123, v123, 1.0 op_sel:[1,0,0]
	v_pk_fma_f16 v127, v127, v117, v139
	v_pk_fma_f16 v124, v124, v117, v128
	v_pk_fma_f16 v125, v125, v117, v129
	v_pk_fma_f16 v126, v126, v117, v130
	v_pk_fma_f16 v116, v123, v117, v116
	v_cvt_scalef32_pk_f16_fp8 v117, v112, 1.0
	v_cvt_scalef32_pk_f16_fp8 v112, v112, 1.0 op_sel:[1,0,0]
	v_pk_fma_f16 v112, v112, v118, v120
	v_cvt_scalef32_pk_f16_fp8 v120, v113, 1.0
	v_cvt_scalef32_pk_f16_fp8 v113, v113, 1.0 op_sel:[1,0,0]
	v_pk_fma_f16 v113, v113, v118, v121
	v_cvt_scalef32_pk_f16_fp8 v121, v114, 1.0
	v_cvt_scalef32_pk_f16_fp8 v114, v114, 1.0 op_sel:[1,0,0]
	v_pk_fma_f16 v114, v114, v118, v122
	v_cvt_scalef32_pk_f16_fp8 v122, v115, 1.0
	v_cvt_scalef32_pk_f16_fp8 v115, v115, 1.0 op_sel:[1,0,0]
	v_pk_fma_f16 v115, v115, v118, v116
	v_cvt_scalef32_pk_f16_fp8 v116, v104, 1.0
	v_cvt_scalef32_pk_f16_fp8 v104, v104, 1.0 op_sel:[1,0,0]
	v_pk_fma_f16 v104, v104, v119, v112
	v_cvt_scalef32_pk_f16_fp8 v112, v105, 1.0
	v_cvt_scalef32_pk_f16_fp8 v105, v105, 1.0 op_sel:[1,0,0]
	v_pk_fma_f16 v105, v105, v119, v113
	v_cvt_scalef32_pk_f16_fp8 v113, v106, 1.0
	v_cvt_scalef32_pk_f16_fp8 v106, v106, 1.0 op_sel:[1,0,0]
	v_pk_fma_f16 v106, v106, v119, v114
	v_cvt_scalef32_pk_f16_fp8 v114, v107, 1.0
	v_cvt_scalef32_pk_f16_fp8 v107, v107, 1.0 op_sel:[1,0,0]
	v_pk_fma_f16 v107, v107, v119, v115
	v_cvt_scalef32_pk_f16_fp8 v115, v96, 1.0
	v_cvt_scalef32_pk_f16_fp8 v96, v96, 1.0 op_sel:[1,0,0]
	v_pk_fma_f16 v96, v96, v84, v104
	v_cvt_scalef32_pk_f16_fp8 v104, v97, 1.0
	v_cvt_scalef32_pk_f16_fp8 v97, v97, 1.0 op_sel:[1,0,0]
	v_pk_fma_f16 v117, v117, v118, v127
	v_pk_fma_f16 v120, v120, v118, v124
	v_pk_fma_f16 v121, v121, v118, v125
	v_pk_fma_f16 v122, v122, v118, v126
	v_pk_fma_f16 v97, v97, v84, v105
	v_cvt_scalef32_pk_f16_fp8 v105, v98, 1.0
	v_cvt_scalef32_pk_f16_fp8 v98, v98, 1.0 op_sel:[1,0,0]
	v_pk_fma_f16 v116, v116, v119, v117
	v_pk_fma_f16 v112, v112, v119, v120
	v_pk_fma_f16 v113, v113, v119, v121
	v_pk_fma_f16 v114, v114, v119, v122
	v_pk_fma_f16 v98, v98, v84, v106
	v_cvt_scalef32_pk_f16_fp8 v106, v99, 1.0
	v_cvt_scalef32_pk_f16_fp8 v99, v99, 1.0 op_sel:[1,0,0]
	v_pk_fma_f16 v115, v115, v84, v116
	v_pk_fma_f16 v104, v104, v84, v112
	v_pk_fma_f16 v105, v105, v84, v113
	v_pk_fma_f16 v106, v106, v84, v114
	v_pk_fma_f16 v84, v99, v84, v107
	v_cvt_scalef32_pk_f16_fp8 v99, v92, 1.0
	v_cvt_scalef32_pk_f16_fp8 v92, v92, 1.0 op_sel:[1,0,0]
	v_pk_fma_f16 v92, v92, v85, v96
	v_cvt_scalef32_pk_f16_fp8 v96, v93, 1.0
	v_cvt_scalef32_pk_f16_fp8 v93, v93, 1.0 op_sel:[1,0,0]
	v_pk_fma_f16 v93, v93, v85, v97
	v_cvt_scalef32_pk_f16_fp8 v97, v94, 1.0
	v_cvt_scalef32_pk_f16_fp8 v94, v94, 1.0 op_sel:[1,0,0]
	v_pk_fma_f16 v94, v94, v85, v98
	v_cvt_scalef32_pk_f16_fp8 v98, v95, 1.0
	v_cvt_scalef32_pk_f16_fp8 v95, v95, 1.0 op_sel:[1,0,0]
	v_pk_fma_f16 v99, v99, v85, v115
	v_pk_fma_f16 v96, v96, v85, v104
	v_pk_fma_f16 v97, v97, v85, v105
	v_pk_fma_f16 v98, v98, v85, v106
	v_pk_fma_f16 v84, v95, v85, v84
	v_cvt_scalef32_pk_f16_fp8 v85, v88, 1.0
	v_cvt_scalef32_pk_f16_fp8 v88, v88, 1.0 op_sel:[1,0,0]
	v_pk_fma_f16 v88, v88, v86, v92
	v_cvt_scalef32_pk_f16_fp8 v92, v89, 1.0
	v_cvt_scalef32_pk_f16_fp8 v89, v89, 1.0 op_sel:[1,0,0]
	v_pk_fma_f16 v89, v89, v86, v93
	v_cvt_scalef32_pk_f16_fp8 v93, v90, 1.0
	v_cvt_scalef32_pk_f16_fp8 v90, v90, 1.0 op_sel:[1,0,0]
	v_pk_fma_f16 v90, v90, v86, v94
	v_cvt_scalef32_pk_f16_fp8 v94, v91, 1.0
	v_cvt_scalef32_pk_f16_fp8 v91, v91, 1.0 op_sel:[1,0,0]
	v_pk_fma_f16 v85, v85, v86, v99
	v_pk_fma_f16 v92, v92, v86, v96
	v_pk_fma_f16 v93, v93, v86, v97
	v_pk_fma_f16 v94, v94, v86, v98
	v_pk_fma_f16 v84, v91, v86, v84
	v_cvt_scalef32_pk_f16_fp8 v86, v80, 1.0
	v_pk_fma_f16 v85, v86, v87, v85
	v_cvt_scalef32_pk_f16_fp8 v80, v80, 1.0 op_sel:[1,0,0]
	v_cvt_scalef32_pk_f16_fp8 v86, v81, 1.0
	v_cvt_scalef32_pk_f16_fp8 v81, v81, 1.0 op_sel:[1,0,0]
	v_pk_fma_f16 v80, v80, v87, v88
	v_pk_fma_f16 v81, v81, v87, v89
	v_cvt_scalef32_pk_f16_fp8 v88, v82, 1.0
	v_cvt_scalef32_pk_f16_fp8 v82, v82, 1.0 op_sel:[1,0,0]
	v_cvt_scalef32_pk_f16_fp8 v89, v83, 1.0
	v_cvt_scalef32_pk_f16_fp8 v83, v83, 1.0 op_sel:[1,0,0]
	v_pk_fma_f16 v86, v86, v87, v92
	v_pk_fma_f16 v88, v88, v87, v93
	v_pk_fma_f16 v82, v82, v87, v90
	v_pk_fma_f16 v89, v89, v87, v94
	v_pk_fma_f16 v83, v83, v87, v84
	v_permlane32_swap_b32_e32 v85, v88
	v_permlane32_swap_b32_e32 v80, v82
	v_permlane32_swap_b32_e32 v86, v89
	v_permlane32_swap_b32_e32 v81, v83
	v_pk_add_f16 v84, v85, v88
	v_pk_add_f16 v80, v80, v82
	v_pk_add_f16 v82, v86, v89
	v_pk_add_f16 v81, v81, v83
	s_nop 0
	v_permlane16_swap_b32_e32 v84, v82
	v_permlane16_swap_b32_e32 v80, v81
	v_pk_add_f16 v82, v84, v82
	v_pk_add_f16 v80, v80, v81
	s_ashr_i32 s9, s8, 31
	v_cndmask_b32_e64 v81, v82, v80, s[2:3]
	v_cndmask_b32_e64 v80, v80, v82, s[2:3]
	s_lshl_b64 s[8:9], s[8:9], 11
	v_mov_b32_dpp v81, v81 row_ror:8 row_mask:0xf bank_mask:0xf bound_ctrl:1
	v_pk_add_f16 v81, v81, v80
	s_add_u32 s16, s14, s8
	v_cvt_f32_f16_e32 v80, v81
	v_cvt_f32_f16_sdwa v81, v81 dst_sel:DWORD dst_unused:UNUSED_PAD src0_sel:WORD_1
	s_addc_u32 s17, s15, s9
	s_lshl_b32 s8, s22, 7
	s_ashr_i32 s9, s8, 31
	v_pk_mul_f32 v[80:81], v[80:81], s[10:11] op_sel_hi:[1,0]
	s_lshl_b64 s[8:9], s[8:9], 1
	v_and_b32_sdwa v83, v80, v208 dst_sel:DWORD dst_unused:UNUSED_PAD src0_sel:WORD_1 src1_sel:DWORD
	v_and_b32_sdwa v82, v81, v208 dst_sel:DWORD dst_unused:UNUSED_PAD src0_sel:WORD_1 src1_sel:DWORD
	v_add3_u32 v80, v80, v83, s7
	s_add_u32 s8, s16, s8
	v_add3_u32 v81, v81, v82, s7
	v_lshrrev_b32_e32 v80, 16, v80
	s_addc_u32 s9, s17, s9
	v_and_or_b32 v82, v81, s11, v80
	v_lshl_add_u64 v[80:81], s[8:9], 0, v[194:195]
	s_add_i32 s8, s24, s19
	s_cmpk_gt_i32 s8, 0x3fff
	s_cselect_b32 s26, s6, s8
	s_cselect_b32 s8, s33, 0
	s_add_i32 s27, s8, s25
	v_mov_b32_e32 v203, v195
	s_cmp_gt_i32 s18, 7
	v_lshl_add_u64 v[80:81], v[80:81], 0, v[202:203]
	s_cselect_b64 s[16:17], -1, 0
	s_mov_b32 s22, s25
	s_mov_b32 s8, s24
	global_store_dword v[80:81], v82, off
	s_branch .LBB0_621
